# v59 + FFN chains after a ctx pass: SwiGLU GEMM in two passes (XCD-aligned latent tiles, then context tiles); norm->SwiGLU and SwiGLU->residual grid syncs become XCD-local barriers, context rows go thr
# speedup vs baseline: 1.0139x; 1.0029x over previous
; #define GLOBAL_PTR(T, p) ((T*)(__attribute__((address_space(1))) T*)(launder_u64((unsigned long long)(p))))
; DI const float* in_ptr(const Args& AR, int i) { asm volatile("" : "+s"(i)); return GLOBAL_PTR(const float, AR.in[i]); }
; #define GRID_SYNC() do { nbar += (unsigned)gridDim.x; grid_barrier(barw, nbar); } while (0)
; __global__ void __launch_bounds__(512, 2) fwd_megakernel(Args args) {
;     ...
;     unsigned* barw = GLOBAL_PTR(unsigned, args.ws); unsigned nbar = 0u;
;     grid.sync();
;     if (PM & 1) prologue_a(F, AR, 5, 6);
;     GRID_SYNC();
;     if (PM & 2) prologue_b(F, AR);
;     GRID_SYNC();
; #pragma unroll 1
;     for (int k_ = 0; k_ < 2; ++k_) {
;         if ((k_ == 0) == ((blockIdx.x & 1) != 0)) norm_phase(F, in_ptr(AR, 0), in_ptr(AR, 2), in_ptr(AR, 4), WSP(float, WS_MOD), 0);
;         else prologue_a(F, AR, 0, 5);
;     }
;     GRID_SYNC();
;     enum { T_NOP = 0, T_NORM, T_SWI, T_RES, T_STORE, T_FT, T_POST, T_SGU, T_ATTE, T_ATTO };
; #pragma unroll 1
;     for (int l = 0; l < 4; ++l) {
;         const bool even = (l & 1) == 0; const int li = l >> 1;
; #pragma unroll 1
;         for (int op = 0; op < 14; ++op) {
.LBB0_183:
	s_or_b64 exec, exec, s[4:5]
	s_add_i32 s2, 0, 0x12000
	v_writelane_b32 v255, s2, 29
	s_add_i32 s2, 0, 0x18810
	s_mov_b64 s[36:37], 0
	s_mov_b32 s21, 0
	s_mov_b32 s96, 0x3e38aa3b
	v_mov_b32_e32 v1, 0
	v_mov_b32_e32 v162, 0x358637bd
	s_mov_b32 s27, 0x800000
	s_mov_b32 s48, 0xf800000
	v_mov_b32_e32 v187, 0x260
	s_mov_b64 s[24:25], 0x80
	v_writelane_b32 v255, s2, 30
	s_movk_i32 s38, 0x1600
	v_mov_b32_e32 v193, 1
	s_barrier
	s_mov_b32 s98, 0
	s_mov_b32 s100, 0
	s_mov_b32 s99, 0
	s_nop 0
	v_writelane_b32 v255, s99, 60
	v_writelane_b32 v255, s99, 61
	v_writelane_b32 v255, s99, 62
	s_mov_b32 s101, 0x880f
	s_branch .LBB0_185

; __global__ void __launch_bounds__(512, 2) fwd_megakernel(Args args) {
;     ...
;             } else if (type == T_RES) {
;                 pg8::Gemm g; pg8::EpiResid E; E.srcL = srcL; E.srcC = srcC; E.dstL = F.out; E.dstC = XC;
;                 if (op == 10) { g = pg8::Gemm{H, WSP(bf16_t, WS_WOUT) + (size_t)l * DM * DM, DM, DM, DM, 0, 0}; E.gate = modl + 1 * 3072 + 2048; E.coef = 1.0f; }
;                 else { const int fi = l * 2 + (op == 2 ? 0 : 1), sub = op == 2 ? 0 : 2; g = pg8::Gemm{BIG, WSP(bf16_t, WS_WD) + (size_t)fi * DM * DFF, DFF, DFF, DFF, 0, 0}; E.gate = modl + sub * 3072 + 2048; E.coef = 0.5f; }
;                 pg8::Order S; S.init(nMt, DM / 256, 1, F.G, bx);
;                 if (PM & 16) pg8::gemm_phase(F.lds, F.tid, g, S, E);
.Lres_go:
	s_cmp_eq_u32 s98, 1
	s_cbranch_scc0 .Lres_nowd
	v_readlane_b32 s33, v255, 62
	s_lshl_b32 s33, s33, 8
	s_mov_b64 s[30:31], exec
	v_readlane_b32 s40, v255, 3
	v_readlane_b32 s41, v255, 4
	s_and_b64 s[40:41], s[30:31], s[40:41]
	s_mov_b64 exec, s[40:41]
	s_cbranch_execz .Lwd_D
.Lwp_D:
	global_load_dword v0, v1, s[14:15] offset:196 sc1
	s_waitcnt vmcnt(0)
	v_cmp_gt_u32_e32 vcc, s33, v0
	s_cbranch_vccz .Lwi_D
	s_sleep 2
	s_branch .Lwp_D

; __global__ void __launch_bounds__(512, 2) fwd_megakernel(Args args) {
;     ...
;             } else if (type == T_RES) {
;                 pg8::Gemm g; pg8::EpiResid E; E.srcL = srcL; E.srcC = srcC; E.dstL = F.out; E.dstC = XC;
;                 if (op == 10) { g = pg8::Gemm{H, WSP(bf16_t, WS_WOUT) + (size_t)l * DM * DM, DM, DM, DM, 0, 0}; E.gate = modl + 1 * 3072 + 2048; E.coef = 1.0f; }
;                 else { const int fi = l * 2 + (op == 2 ? 0 : 1), sub = op == 2 ? 0 : 2; g = pg8::Gemm{BIG, WSP(bf16_t, WS_WD) + (size_t)fi * DM * DFF, DFF, DFF, DFF, 0, 0}; E.gate = modl + sub * 3072 + 2048; E.coef = 0.5f; }
;                 pg8::Order S; S.init(nMt, DM / 256, 1, F.G, bx);
;                 if (PM & 16) pg8::gemm_phase(F.lds, F.tid, g, S, E);
.Lwd_D:
	s_mov_b64 exec, s[30:31]
	s_barrier

; DI const char* a_of(const Gemm& g, const Unit& u) { return (const char*)(g.A + (size_t)u.pz * g.zA + (size_t)u.pm * BM * g.lda); }
; DI const char* b_of(const Gemm& g, const Unit& u) { return (const char*)(g.Bt + (size_t)u.pz * g.zB + (size_t)u.pn * BM * g.ldb); }
; template <class Epi>
; DI void gemm_phase(LAS unsigned char* lds, int tid, const Gemm g, const Order& S, const Epi& E) {
;     const int wid = __builtin_amdgcn_readfirstlane(tid >> 6), lane = tid & 63, wr = wid >> 2, wc = wid & 3, fr = lane & 15, fq = lane >> 4;
;     const int K = g.K, nt = K / BK;
;     unsigned voffA[2], voffB[2];
; #pragma unroll
;     for (int i = 0; i < 2; ++i) { int R, C; stage_rc(tid * 16 + i * 8192, R, C); const int Rb = (R & ~31) + perm32(R & 31);
;         voffA[i] = (unsigned)(R * g.lda + C) * 2u; voffB[i] = (unsigned)(Rb * g.ldb + C) * 2u; }
;     const size_t kstep = (size_t)(BK * 2);
;     const size_t hstepA = (size_t)HALF * g.lda * 2, hstepB = (size_t)HALF * g.ldb * 2;
;     const unsigned ldsw = (unsigned)wid * 1024u;
;     const int aoff = lds_byte(wr * 64 + fr, fq * 8), boff = lds_byte(wc * 32 + fr, fq * 8);
;     ...
;     __syncthreads();
;     Unit cur, nxt; int ui = 0;
;     if (!S.next(0, cur)) return;
;     f32x4 acc[2][2][4][2];
; #pragma unroll
;     for (int a = 0; a < 2; ++a)
; #pragma unroll
;         for (int b = 0; b < 2; ++b)
; #pragma unroll
;             for (int m = 0; m < 4; ++m)
; #pragma unroll
;                 for (int n = 0; n < 2; ++n) acc[a][b][m][n] = (f32x4){0.f, 0.f, 0.f, 0.f};
;     bf16x8 At[4][2], B0[2][2], B1[2][2];
;     const char* cA = a_of(g, cur); const char* cB = b_of(g, cur);
;     PG8_STAGE(PG8_SB(0, 0), cB, voffB); PG8_STAGE(PG8_SB(0, 1), cB + hstepB, voffB); PG8_STAGE(PG8_SA(0, 0), cA, voffA); PG8_STAGE(PG8_SA(0, 1), cA + hstepA, voffA);
;     if (wr == 1) PG8_BAR;
;     PG8_WAIT_V(2); PG8_BAR;
;     PG8_STAGE(PG8_SB(1, 0), cB + kstep, voffB); PG8_STAGE(PG8_SA(1, 0), cA + kstep, voffA); PG8_STAGE(PG8_SB(1, 1), cB + hstepB + kstep, voffB);
;     PG8_WAIT_V(6); PG8_BAR;
; __global__ void __launch_bounds__(512, 2) fwd_megakernel(Args args) {
;     ...
;                 const int fi = l * 2 + (op == 1 ? 0 : 1);
;                 pg8::Gemm g{H, WSP(bf16_t, WS_WGU) + (size_t)fi * 2 * DFF * DM, DM, DM, DM, 0, 0}; pg8::Order S; S.init(nMt, 2 * DFF / 256, 1, F.G, bx);
;                 pg8::EpiSwiGLU E{BIG};
.LBB0_503:
	s_cmp_gt_i32 s35, 1
	s_mov_b64 s[4:5], -1
	s_cbranch_scc0 .LBB0_522
	s_cmp_eq_u32 s98, 3
	s_cbranch_scc0 .Lsw_n3
	s_movk_i32 s42, 0x100
.Lsw_n3:
	s_cmp_eq_u32 s98, 4
	s_cbranch_scc0 .Lsw_n4
	s_movk_i32 s42, 16
	s_add_u32 s58, s58, 0x8000000
	s_addc_u32 s59, s59, 0
	s_add_u32 s62, s62, 0x16000000
	s_addc_u32 s63, s63, 0
.Lsw_n4:
	s_mul_i32 s20, s42, 22
	s_cmp_ge_i32 s2, s20
	v_readfirstlane_b32 s5, v164
	s_waitcnt vmcnt(0) lgkmcnt(0)
	s_barrier
	s_cbranch_scc1 .LBB0_521
	v_ashrrev_i32_e32 v4, 31, v164
	v_lshrrev_b32_e32 v4, 26, v4
	v_lshlrev_b32_e32 v0, 4, v164
	v_add_u32_e32 v4, v164, v4
	v_ashrrev_i32_e32 v11, 6, v4
	v_ashrrev_i32_e32 v4, 31, v0
	v_lshrrev_b32_e32 v4, 22, v4
	v_add_u32_e32 v4, v0, v4
	v_and_b32_e32 v4, 0xfffffc00, v4
	v_add_u32_e32 v2, 0x2000, v0
	v_sub_u32_e32 v0, v0, v4
	v_ashrrev_i32_e32 v3, 31, v2
	s_cmp_eq_u32 s44, 1
	v_lshrrev_b32_e32 v4, 4, v0
	v_lshrrev_b32_e32 v3, 22, v3
	s_cselect_b32 s4, 0, 2
	v_readlane_b32 s6, v255, 40
	v_bitop3_b32 v4, v4, v0, 32 bitop3:0x6c
	v_ashrrev_i32_e32 v0, 31, v0
	v_add_u32_e32 v3, v2, v3
	s_or_b32 s4, s4, s6
	v_lshrrev_b32_e32 v0, 26, v0
	v_ashrrev_i32_e32 v10, 10, v3
	s_mul_i32 s6, s4, 0x2c0000
	s_mov_b32 s7, s21
	v_add_u32_e32 v0, v4, v0
	v_mul_i32_i24_e32 v3, 0x400, v10
	s_lshl_b64 s[6:7], s[6:7], 1
	v_lshlrev_b32_e32 v5, 3, v11
	v_ashrrev_i32_e32 v12, 6, v0
	v_and_b32_e32 v0, 0xc0, v0
	s_add_u32 s4, s60, s6
	v_and_b32_e32 v5, -16, v5
	v_sub_u32_e32 v0, v4, v0
	v_sub_u32_e32 v2, v2, v3
	s_addc_u32 s6, s61, s7
	v_add_u32_e32 v5, v12, v5
	v_ashrrev_i16_sdwa v0, v193, sext(v0) dst_sel:DWORD dst_unused:UNUSED_PAD src0_sel:DWORD src1_sel:BYTE_0
	v_lshrrev_b32_e32 v3, 4, v2
	s_add_u32 s10, s4, 0x1b00000
	v_lshlrev_b32_e32 v6, 5, v11
	v_bfe_i32 v13, v0, 0, 16
	v_lshlrev_b32_e32 v0, 1, v5
	v_lshrrev_b32_e32 v4, 2, v5
	v_and_b32_e32 v7, 3, v12
	s_mov_b32 s4, 0x1fffe0
	v_bitop3_b32 v3, v3, v2, 32 bitop3:0x6c
	v_ashrrev_i32_e32 v2, 31, v2
	v_and_b32_e32 v6, 32, v6
	v_and_b32_e32 v0, 24, v0
	v_and_b32_e32 v4, 4, v4
	v_and_or_b32 v7, v5, s4, v7
	v_lshrrev_b32_e32 v2, 26, v2
	v_or3_b32 v0, v7, v4, v0
	v_add_lshl_u32 v4, v6, v13, 1
	v_add_u32_e32 v2, v3, v2
	v_lshl_add_u32 v130, v5, 11, v4
	v_lshl_add_u32 v0, v0, 11, v4
	v_lshlrev_b32_e32 v4, 3, v10
	v_ashrrev_i32_e32 v14, 6, v2
	v_and_b32_e32 v2, 0xc0, v2
	v_and_b32_e32 v4, -16, v4
	v_sub_u32_e32 v2, v3, v2
	v_add_u32_e32 v4, v14, v4
	v_ashrrev_i16_sdwa v2, v193, sext(v2) dst_sel:DWORD dst_unused:UNUSED_PAD src0_sel:DWORD src1_sel:BYTE_0
	v_lshlrev_b32_e32 v5, 5, v10
	v_bfe_i32 v15, v2, 0, 16
	v_lshlrev_b32_e32 v2, 1, v4
	v_lshrrev_b32_e32 v3, 2, v4
	v_and_b32_e32 v6, 3, v14
	v_and_b32_e32 v5, 32, v5
	v_and_b32_e32 v2, 24, v2
	v_and_b32_e32 v3, 4, v3
	v_and_or_b32 v6, v4, s4, v6
	v_or3_b32 v2, v6, v3, v2
	v_add_lshl_u32 v3, v5, v15, 1
	v_lshl_add_u32 v134, v2, 11, v3
	v_cvt_f32_u32_e32 v2, s20
	s_addc_u32 s11, s6, 0
	s_ashr_i32 s18, s2, 31
	s_lshr_b32 s4, s18, 29
	v_rcp_iflag_f32_e32 v2, v2
	s_add_i32 s4, s2, s4
	s_ashr_i32 s6, s4, 3
	s_and_b32 s4, s4, -8
	v_mul_f32_e32 v2, 0x4f7ffffe, v2
	v_cvt_u32_f32_e32 v2, v2
	s_sub_i32 s4, s2, s4
	s_lshr_b32 s16, s20, 3
	s_lshr_b32 s7, s4, 31
	s_or_b32 s7, s16, s7
	s_mul_i32 s4, s4, s7
	s_sub_i32 s7, 0, s20
	v_readfirstlane_b32 s19, v2
	s_mul_i32 s7, s7, s19
	s_add_i32 s4, s4, s6
	s_mul_hi_u32 s7, s19, s7
	s_ashr_i32 s6, s4, 31
	s_abs_i32 s4, s4
	s_add_i32 s19, s19, s7
	s_mul_hi_u32 s7, s4, s19
	s_mul_i32 s7, s7, s20
	s_ashr_i32 s9, s5, 6
	s_sub_i32 s4, s4, s7
	s_ashr_i32 s8, s5, 8
	s_lshl_b32 s17, s9, 10
	s_sub_i32 s7, s4, s20
	s_cmp_ge_u32 s4, s20
	s_cselect_b32 s4, s7, s4
	s_sub_i32 s7, s4, s20
	s_cmp_ge_u32 s4, s20
	s_cselect_b32 s4, s7, s4
	s_xor_b32 s4, s4, s6
	s_sub_i32 s4, s4, s6
	s_sext_i32_i16 s6, s4
	s_mulk_i32 s6, 0xba3
	s_lshr_b32 s7, s6, 31
	s_ashr_i32 s6, s6, 18
	s_add_i32 s6, s6, s7
	s_lshl_b32 s22, s6, 2
	s_sub_i32 s7, s42, s22
	s_min_i32 s26, s7, 4
	s_sext_i32_i8 s7, s26
	v_cvt_f32_i32_e32 v2, s7
	s_mulk_i32 s6, 0x58
	s_sub_i32 s4, s4, s6
	s_sext_i32_i16 s28, s4
	v_lshl_add_u32 v132, v4, 11, v3
	v_cvt_f32_i32_e32 v3, s28
	v_rcp_iflag_f32_e32 v4, v2
	s_xor_b32 s4, s28, s7
	s_ashr_i32 s4, s4, 30
	s_or_b32 s4, s4, 1
	v_mul_f32_e32 v4, v3, v4
	v_trunc_f32_e32 v4, v4
	v_fma_f32 v3, -v4, v2, v3
	v_cvt_i32_f32_e32 v4, v4
	v_cmp_ge_f32_e64 s[6:7], |v3|, |v2|
	s_and_b64 s[6:7], s[6:7], exec
	s_cselect_b32 s4, s4, 0
	v_readfirstlane_b32 s6, v4
	s_add_i32 s4, s6, s4
	s_mul_i32 s6, s4, s26
	s_sub_i32 s6, s28, s6
	s_sext_i32_i8 s6, s6
	s_add_i32 s72, s22, s6
	s_ashr_i32 s73, s72, 31
	s_bfe_i64 s[30:31], s[4:5], 0x80000
	s_lshl_b64 s[6:7], s[72:73], 19
	s_lshl_b64 s[30:31], s[30:31], 19
	s_add_u32 s76, s10, s30
	s_addc_u32 s77, s11, s31
	s_add_i32 s22, s17, 0
	s_add_i32 m0, s22, 0x10000
	v_mov_b32_e32 v135, v1
	global_load_lds_dwordx4 v0, s[76:77]
	s_add_i32 m0, s22, 0x12000
	s_add_u32 s30, s76, 0x40000
	global_load_lds_dwordx4 v134, s[76:77]
	s_addc_u32 s31, s77, 0
	s_add_i32 m0, s22, 0x14000
	v_mov_b32_e32 v131, v1
	global_load_lds_dwordx4 v0, s[30:31]
	s_add_i32 m0, s22, 0x16000
	s_add_u32 s74, s58, s6
	s_addc_u32 s75, s59, s7
	s_add_i32 s26, s22, 0x2000
	global_load_lds_dwordx4 v134, s[30:31]
	s_mov_b32 m0, s22
	s_add_u32 s6, s74, 0x40000
	global_load_lds_dwordx4 v130, s[74:75]
	s_mov_b32 m0, s26
	s_addc_u32 s7, s75, 0
	s_add_i32 s28, s22, 0x4000
	global_load_lds_dwordx4 v132, s[74:75]
	s_mov_b32 m0, s28
	s_add_i32 s30, s22, 0x6000
	global_load_lds_dwordx4 v130, s[6:7]
	s_mov_b32 m0, s30
	v_mov_b32_e32 v133, v1
	global_load_lds_dwordx4 v132, s[6:7]
	s_cmp_eq_u32 s8, 1
	v_lshl_add_u64 v[8:9], s[76:77], 0, v[0:1]
	v_lshl_add_u64 v[6:7], s[76:77], 0, v[134:135]
	v_lshl_add_u64 v[2:3], s[74:75], 0, v[130:131]
	s_cselect_b64 s[6:7], -1, 0
	s_cmp_lg_u32 s8, 1
	v_lshl_add_u64 v[4:5], s[74:75], 0, v[132:133]
	s_cbranch_scc1 .LBB0_507
	s_barrier

; DI const float* in_ptr(const Args& AR, int i) { asm volatile("" : "+s"(i)); return GLOBAL_PTR(const float, AR.in[i]); }
; DI void grid_barrier(unsigned* cnt, unsigned target) {
;     asm volatile("s_waitcnt vmcnt(0) lgkmcnt(0)" ::: "memory");
;     __syncthreads();
;     if (threadIdx.x == 0) {
;         __builtin_amdgcn_fence(__ATOMIC_RELEASE, "agent");
;         asm volatile("s_waitcnt vmcnt(0)" ::: "memory");
;         __hip_atomic_fetch_add(cnt, 1u, __ATOMIC_RELAXED, __HIP_MEMORY_SCOPE_AGENT);
;         while (__hip_atomic_load(cnt, __ATOMIC_RELAXED, __HIP_MEMORY_SCOPE_AGENT) < target) __builtin_amdgcn_s_sleep(2);
;         __builtin_amdgcn_fence(__ATOMIC_ACQUIRE, "agent");
;         asm volatile("s_waitcnt vmcnt(0)" ::: "memory");
;     }
;     __syncthreads();
; }
; __global__ void __launch_bounds__(512, 2) fwd_megakernel(Args args) {
;     ...
;             if (type == T_NORM) {
;                 const int sub = op == 0 ? 0 : (op == 3 ? 1 : 2);
;                 if (even && op == 3) norm_pair_phase(F, srcL, srcC, in_ptr(AR, 4) + (size_t)(l * 3 + sub) * DM, modl, sub);
;                 else norm_phase(F, srcL, srcC, in_ptr(AR, 4) + (size_t)(l * 3 + sub) * DM, modl, sub);
;             } else if (type == T_SWI) {
;                 const int fi = l * 2 + (op == 1 ? 0 : 1);
;                 pg8::Gemm g{H, WSP(bf16_t, WS_WGU) + (size_t)fi * 2 * DFF * DM, DM, DM, DM, 0, 0}; pg8::Order S; S.init(nMt, 2 * DFF / 256, 1, F.G, bx);
;                 pg8::EpiSwiGLU E{BIG};
; #pragma unroll 1
;                 for (int rep_ = 0; rep_ < ((REP & 4) ? 2 : 1); ++rep_) pg8::gemm_phase(F.lds, F.tid, g, S, E);
.Lcs_b_normal:
	s_cmp_eq_u32 s98, 2
	s_cbranch_scc0 .Lch_not2
	s_cmp_eq_u32 s44, 0
	s_cbranch_scc1 .Lch_start
	s_cmp_eq_u32 s44, 11
	s_cbranch_scc0 .Lxl_pre
.Lch_start:
	s_waitcnt vmcnt(0) lgkmcnt(0)
	s_barrier
	v_readlane_b32 s10, v255, 61
	s_add_u32 s10, s10, 1
	s_nop 0
	v_writelane_b32 v255, s10, 61
	s_mov_b64 s[4:5], exec
	v_readlane_b32 s6, v255, 3
	v_readlane_b32 s7, v255, 4
	s_and_b64 s[6:7], s[4:5], s[6:7]
	s_mov_b64 exec, s[6:7]
	s_cbranch_execz .Lar_C
	buffer_wbl2 sc1
	s_waitcnt vmcnt(0)
	v_mov_b32_e32 v0, 1
	global_atomic_add v1, v0, s[14:15] offset:192
.Lar_C:
	s_mov_b64 exec, s[4:5]
	v_readlane_b32 s10, v255, 60
	s_add_u32 s10, s10, 1
	s_nop 0
	v_writelane_b32 v255, s10, 60
	s_lshl_b32 s10, s10, 5
	v_readlane_b32 s2, v255, 0
	s_mov_b64 s[4:5], exec
	v_readlane_b32 s6, v255, 3
	v_readlane_b32 s7, v255, 4
	s_and_b64 s[6:7], s[4:5], s[6:7]
	s_mov_b64 exec, s[6:7]
	s_cbranch_execz .Llb_Y
	s_and_b32 s3, s2, 7
	s_lshl_b32 s3, s3, 2
	s_add_u32 s8, s14, s3
	s_addc_u32 s9, s15, 0
	v_mov_b32_e32 v0, 1
	global_atomic_add v1, v0, s[8:9] offset:128
.Llp_Y:
	global_load_dword v0, v1, s[8:9] offset:128 sc1
	s_waitcnt vmcnt(0)
	v_cmp_gt_u32_e32 vcc, s10, v0
	s_cbranch_vccz .Lli_Y
	s_sleep 1
	s_branch .Llp_Y
.Lli_Y:
	buffer_inv sc1
	s_waitcnt vmcnt(0)
.Llb_Y:
	s_mov_b64 exec, s[4:5]
	s_barrier
	s_mov_b32 s98, 3
	s_branch .LBB0_585
.Lch_not2:
	s_cmp_eq_u32 s98, 3
	s_cbranch_scc0 .Lch_not3
	v_readlane_b32 s10, v255, 61
	s_lshl_b32 s10, s10, 8
	s_mov_b64 s[4:5], exec
	v_readlane_b32 s6, v255, 3
	v_readlane_b32 s7, v255, 4
	s_and_b64 s[6:7], s[4:5], s[6:7]
	s_mov_b64 exec, s[6:7]
	s_cbranch_execz .Lwd_C
.Lwp_C:
	global_load_dword v0, v1, s[14:15] offset:192 sc1
	s_waitcnt vmcnt(0)
	v_cmp_gt_u32_e32 vcc, s10, v0
	s_cbranch_vccz .Lwi_C
	s_sleep 2
	s_branch .Lwp_C

; DI const float* in_ptr(const Args& AR, int i) { asm volatile("" : "+s"(i)); return GLOBAL_PTR(const float, AR.in[i]); }
; DI void grid_barrier(unsigned* cnt, unsigned target) {
;     asm volatile("s_waitcnt vmcnt(0) lgkmcnt(0)" ::: "memory");
;     __syncthreads();
;     if (threadIdx.x == 0) {
;         __builtin_amdgcn_fence(__ATOMIC_RELEASE, "agent");
;         asm volatile("s_waitcnt vmcnt(0)" ::: "memory");
;         __hip_atomic_fetch_add(cnt, 1u, __ATOMIC_RELAXED, __HIP_MEMORY_SCOPE_AGENT);
;         while (__hip_atomic_load(cnt, __ATOMIC_RELAXED, __HIP_MEMORY_SCOPE_AGENT) < target) __builtin_amdgcn_s_sleep(2);
;         __builtin_amdgcn_fence(__ATOMIC_ACQUIRE, "agent");
;         asm volatile("s_waitcnt vmcnt(0)" ::: "memory");
;     }
;     __syncthreads();
; }
; __global__ void __launch_bounds__(512, 2) fwd_megakernel(Args args) {
;     ...
;             if (type == T_NORM) {
;                 const int sub = op == 0 ? 0 : (op == 3 ? 1 : 2);
;                 if (even && op == 3) norm_pair_phase(F, srcL, srcC, in_ptr(AR, 4) + (size_t)(l * 3 + sub) * DM, modl, sub);
;                 else norm_phase(F, srcL, srcC, in_ptr(AR, 4) + (size_t)(l * 3 + sub) * DM, modl, sub);
;             } else if (type == T_SWI) {
;                 const int fi = l * 2 + (op == 1 ? 0 : 1);
;                 pg8::Gemm g{H, WSP(bf16_t, WS_WGU) + (size_t)fi * 2 * DFF * DM, DM, DM, DM, 0, 0}; pg8::Order S; S.init(nMt, 2 * DFF / 256, 1, F.G, bx);
;                 pg8::EpiSwiGLU E{BIG};
; #pragma unroll 1
;                 for (int rep_ = 0; rep_ < ((REP & 4) ? 2 : 1); ++rep_) pg8::gemm_phase(F.lds, F.tid, g, S, E);
.Lwd_C:
	s_mov_b64 exec, s[4:5]
	s_barrier
	s_mov_b32 s98, 4
	s_mov_b32 s48, 0xf800000
	s_branch .LBB0_188
.Lch_not3:
	s_cmp_eq_u32 s98, 4
	s_cbranch_scc0 .Lxl_pre
	s_waitcnt vmcnt(0) lgkmcnt(0)
	s_barrier
	v_readlane_b32 s10, v255, 62
	s_add_u32 s10, s10, 1
	s_nop 0
	v_writelane_b32 v255, s10, 62
	s_mov_b64 s[4:5], exec
	v_readlane_b32 s6, v255, 3
	v_readlane_b32 s7, v255, 4
	s_and_b64 s[6:7], s[4:5], s[6:7]
	s_mov_b64 exec, s[6:7]
	s_cbranch_execz .Lar_D
	buffer_wbl2 sc1
	s_waitcnt vmcnt(0)
	v_mov_b32_e32 v0, 1
	global_atomic_add v1, v0, s[14:15] offset:196

; DI void grid_barrier(unsigned* cnt, unsigned target) {
;     asm volatile("s_waitcnt vmcnt(0) lgkmcnt(0)" ::: "memory");
;     __syncthreads();
;     if (threadIdx.x == 0) {
;         __builtin_amdgcn_fence(__ATOMIC_RELEASE, "agent");
;         asm volatile("s_waitcnt vmcnt(0)" ::: "memory");
;         __hip_atomic_fetch_add(cnt, 1u, __ATOMIC_RELAXED, __HIP_MEMORY_SCOPE_AGENT);
;         while (__hip_atomic_load(cnt, __ATOMIC_RELAXED, __HIP_MEMORY_SCOPE_AGENT) < target) __builtin_amdgcn_s_sleep(2);
;         __builtin_amdgcn_fence(__ATOMIC_ACQUIRE, "agent");
;         asm volatile("s_waitcnt vmcnt(0)" ::: "memory");
;     }
;     __syncthreads();
; }
.Llp_S:
	global_load_dword v0, v1, s[8:9] offset:128 sc1
	s_waitcnt vmcnt(0)
	v_cmp_gt_u32_e32 vcc, s10, v0
	s_cbranch_vccz .Lli_S
	s_sleep 1
	s_branch .Llp_S
.Lli_S:
	buffer_inv sc1
	s_waitcnt vmcnt(0)
.Llb_S:
	s_mov_b64 exec, s[4:5]
	s_barrier
	s_mov_b32 s98, 5
	s_branch .LBB0_585
